# attention step: counted vmcnt(4)/(2) instead of vmcnt(0) before LDS ring writes and Q copy (2-step-deep K/V prefetch as source intended)
# speedup vs baseline: 1.0078x; 1.0078x over previous
.LBB0_122:
	s_waitcnt vmcnt(4)
	ds_write_b128 v95, v[48:51]
	s_waitcnt vmcnt(4)
	ds_write_b128 v96, v[52:55]
	s_waitcnt lgkmcnt(0)
	s_barrier
	s_add_i32 s3, s3, 3
	s_cmpk_gt_u32 s3, 0x89
	s_cbranch_scc1 .LBB0_110

.LBB0_128:
	s_cmp_eq_u32 s1, 15
	s_cselect_b32 s16, 0, 0x80
	s_waitcnt vmcnt(2)
	v_or_b32_e32 v0, s16, v63
	v_add_u32_e32 v0, s2, v0
	v_ashrrev_i32_e32 v1, 31, v0
	v_lshlrev_b64 v[0:1], 12, v[0:1]
	s_waitcnt vmcnt(2)
	v_lshl_add_u64 v[4:5], v[74:75], 0, v[0:1]
	global_load_dwordx4 v[0:3], v[4:5], off
	s_nop 0
	global_load_dwordx4 v[4:7], v[4:5], off offset:64

.LBB0_133:
	s_cmp_lt_i32 s4, 16
	s_cselect_b32 s18, s15, 0
	v_add_u32_e32 v102, 0x1b000, v92
	s_ashr_i32 s19, s18, 31
	s_waitcnt vmcnt(4)
	ds_write_b128 v102, v[28:31]
	v_add_u32_e32 v28, 0x1d400, v92
	s_lshl_b64 s[20:21], s[18:19], 18
	s_lshl_b32 s18, s18, 6
	ds_write_b128 v28, v[16:19]
	s_ashr_i32 s19, s18, 31
	s_waitcnt lgkmcnt(0)
	s_barrier
	v_lshl_add_u64 v[16:17], v[70:71], 0, s[20:21]
	v_lshl_add_u64 v[18:19], s[18:19], 1, v[72:73]
	global_load_dwordx4 v[28:31], v[16:17], off offset:2048
	s_nop 0
	global_load_dwordx4 v[16:19], v[18:19], off
	s_add_i32 s17, s17, 1
	v_cmp_lt_i32_e32 vcc, s17, v98
	s_cbranch_vccnz .LBB0_135
	s_add_i32 s4, s4, 1
	s_lshl_b32 s15, s4, 1
	v_med3_i32 v98, s15, 4, 28
	s_or_b32 s15, s15, 1
	v_med3_i32 v102, s15, 4, 28
	v_readfirstlane_b32 s16, v98
	v_sub_u32_e32 v98, v102, v98
	s_add_i32 s16, s16, -4
	v_add_u32_e32 v98, 8, v98
	s_mov_b32 s17, 0
	s_cmp_gt_i32 s1, 15
	s_cbranch_scc0 .LBB0_136
	s_branch .LBB0_143

.LBB0_138:
	s_cmp_eq_u32 s1, 15
	s_cselect_b32 s15, 0, 0x80
	s_add_i32 s15, s15, s2
	s_waitcnt vmcnt(2)
	v_add_u32_e32 v0, s15, v63
	v_ashrrev_i32_e32 v1, 31, v0
	v_lshlrev_b64 v[0:1], 12, v[0:1]
	s_waitcnt vmcnt(2)
	v_lshl_add_u64 v[4:5], v[74:75], 0, v[0:1]
	global_load_dwordx4 v[0:3], v[4:5], off
	s_nop 0
	global_load_dwordx4 v[4:7], v[4:5], off offset:64

.LBB0_143:
	s_cmp_lt_i32 s4, 16
	s_cselect_b32 s18, s16, 0
	s_ashr_i32 s19, s18, 31
	s_lshl_b64 s[20:21], s[18:19], 18
	s_lshl_b32 s18, s18, 6
	s_waitcnt vmcnt(4)
	ds_write_b128 v93, v[24:27]
	ds_write_b128 v94, v[20:23]
	s_ashr_i32 s19, s18, 31
	s_waitcnt lgkmcnt(0)
	s_barrier
	v_lshl_add_u64 v[20:21], v[70:71], 0, s[20:21]
	v_lshl_add_u64 v[22:23], s[18:19], 1, v[72:73]
	global_load_dwordx4 v[24:27], v[20:21], off offset:2048
	s_nop 0
	global_load_dwordx4 v[20:23], v[22:23], off
	s_add_i32 s15, s17, 1
	v_cmp_lt_i32_e32 vcc, s15, v98
	s_cbranch_vccnz .LBB0_145
	s_add_i32 s4, s4, 1
	s_lshl_b32 s15, s4, 1
	v_med3_i32 v98, s15, 4, 28
	s_or_b32 s15, s15, 1
	v_med3_i32 v102, s15, 4, 28
	v_readfirstlane_b32 s16, v98
	v_sub_u32_e32 v98, v102, v98
	s_add_i32 s16, s16, -4
	v_add_u32_e32 v98, 8, v98
	s_mov_b32 s15, 0
	s_cmp_gt_i32 s1, 15
	s_cbranch_scc1 .LBB0_122
	s_branch .LBB0_146

.LBB0_148:
	s_cmp_eq_u32 s1, 15
	s_cselect_b32 s17, 0, 0x80
	s_add_i32 s17, s17, s2
	s_waitcnt vmcnt(2)
	v_add_u32_e32 v0, s17, v63
	v_ashrrev_i32_e32 v1, 31, v0
	v_lshlrev_b64 v[0:1], 12, v[0:1]
	s_waitcnt vmcnt(2)
	v_lshl_add_u64 v[4:5], v[74:75], 0, v[0:1]
	global_load_dwordx4 v[0:3], v[4:5], off
	s_nop 0
	global_load_dwordx4 v[4:7], v[4:5], off offset:64

.LBB0_159:
	v_mov_b32_e32 v100, 0
	s_waitcnt vmcnt(2)
	v_mov_b64_e32 v[14:15], v[6:7]
	v_mov_b32_e32 v101, 0xf149f2ca
	v_mov_b64_e32 v[12:13], v[4:5]
	v_mov_b64_e32 v[10:11], v[2:3]
	v_mov_b64_e32 v[8:9], v[0:1]
	v_mov_b32_e32 v32, 0
	v_mov_b32_e32 v33, v100
	v_mov_b32_e32 v34, v100
	v_mov_b32_e32 v35, v100
	v_mov_b32_e32 v36, v100
	v_mov_b32_e32 v37, v100
	v_mov_b32_e32 v38, v100
	v_mov_b32_e32 v39, v100
	v_mov_b32_e32 v40, v100
	v_mov_b32_e32 v41, v100
	v_mov_b32_e32 v42, v100
	v_mov_b32_e32 v43, v100
	v_mov_b32_e32 v44, v100
	v_mov_b32_e32 v45, v100
	v_mov_b32_e32 v46, v100
	v_mov_b32_e32 v47, v100
	s_add_i32 s16, s5, -2
	s_cmp_lg_u32 s14, s16
	s_cbranch_scc0 .LBB0_128
	s_branch .LBB0_129
.LBB0_160:
	v_mov_b32_e32 v100, 0
	s_waitcnt vmcnt(2)
	v_mov_b64_e32 v[14:15], v[6:7]
	v_mov_b32_e32 v101, 0xf149f2ca
	v_mov_b64_e32 v[12:13], v[4:5]
	v_mov_b64_e32 v[10:11], v[2:3]
	v_mov_b64_e32 v[8:9], v[0:1]
	v_mov_b32_e32 v32, 0
	v_mov_b32_e32 v33, v100
	v_mov_b32_e32 v34, v100
	v_mov_b32_e32 v35, v100
	v_mov_b32_e32 v36, v100
	v_mov_b32_e32 v37, v100
	v_mov_b32_e32 v38, v100
	v_mov_b32_e32 v39, v100
	v_mov_b32_e32 v40, v100
	v_mov_b32_e32 v41, v100
	v_mov_b32_e32 v42, v100
	v_mov_b32_e32 v43, v100
	v_mov_b32_e32 v44, v100
	v_mov_b32_e32 v45, v100
	v_mov_b32_e32 v46, v100
	v_mov_b32_e32 v47, v100
	s_add_i32 s15, s5, -2
	s_cmp_lg_u32 s14, s15
	s_cbranch_scc0 .LBB0_138
	s_branch .LBB0_139
.LBB0_161:
	v_mov_b32_e32 v100, 0
	s_waitcnt vmcnt(2)
	v_mov_b64_e32 v[14:15], v[6:7]
	v_mov_b32_e32 v101, 0xf149f2ca
	v_mov_b64_e32 v[12:13], v[4:5]
	v_mov_b64_e32 v[10:11], v[2:3]
	v_mov_b64_e32 v[8:9], v[0:1]
	v_mov_b32_e32 v32, 0
	v_mov_b32_e32 v33, v100
	v_mov_b32_e32 v34, v100
	v_mov_b32_e32 v35, v100
	v_mov_b32_e32 v36, v100
	v_mov_b32_e32 v37, v100
	v_mov_b32_e32 v38, v100
	v_mov_b32_e32 v39, v100
	v_mov_b32_e32 v40, v100
	v_mov_b32_e32 v41, v100
	v_mov_b32_e32 v42, v100
	v_mov_b32_e32 v43, v100
	v_mov_b32_e32 v44, v100
	v_mov_b32_e32 v45, v100
	v_mov_b32_e32 v46, v100
	v_mov_b32_e32 v47, v100
	s_add_i32 s17, s5, -2
	s_cmp_lg_u32 s14, s17
	s_cbranch_scc0 .LBB0_148
	s_branch .LBB0_149
